# W_up (P1) and W_down (P7) conversion stores made streaming write-through (sc0 sc1 nt): the converted weights are only read hundreds of microseconds later
# baseline (speedup 1.0000x reference)
.Lmy_wup_begin:
	s_cmpk_lg_u32 s88, 0x100
	s_cbranch_scc1 .Lmy_wup_end
	s_waitcnt lgkmcnt(0)
	s_barrier
	v_readlane_b32 s2, v252, 0
	v_readlane_b32 s3, v252, 1
	s_add_u32 s2, s2, 0xffffff20
	s_addc_u32 s3, s3, -1
	s_load_dwordx4 s[4:7], s[2:3], 0xb0
	v_and_b32_e32 v197, 63, v158
	v_lshrrev_b32_e32 v198, 4, v197
	v_and_b32_e32 v194, 15, v197
	v_lshlrev_b32_e32 v194, 2, v194
	v_mul_u32_u24_e32 v193, 0x4100, v159
	v_mul_u32_u24_e32 v192, 65, v198
	v_add_u32_e32 v192, v192, v194
	v_lshl_add_u32 v176, v192, 2, v193
	v_add_u32_e32 v177, 0x410, v176
	v_add_u32_e32 v178, 0x820, v176
	v_add_u32_e32 v179, 0xc30, v176
	v_add_u32_e32 v180, 0x1040, v176
	v_add_u32_e32 v181, 0x1450, v176
	v_add_u32_e32 v182, 0x1860, v176
	v_add_u32_e32 v183, 0x1c70, v176
	v_add_u32_e32 v184, 0x2080, v176
	v_add_u32_e32 v185, 0x2490, v176
	v_add_u32_e32 v186, 0x28a0, v176
	v_add_u32_e32 v187, 0x2cb0, v176
	v_add_u32_e32 v188, 0x30c0, v176
	v_add_u32_e32 v189, 0x34d0, v176
	v_add_u32_e32 v190, 0x38e0, v176
	v_add_u32_e32 v191, 0x3cf0, v176
	v_lshlrev_b32_e32 v195, 2, v198
	v_lshlrev_b32_e32 v194, 2, v194
	v_lshl_add_u32 v194, v198, 15, v194
	v_and_b32_e32 v196, 7, v197
	v_mul_u32_u24_e32 v192, 0x208, v196
	v_lshrrev_b32_e32 v198, 3, v197
	v_add_u32_e32 v192, v192, v198
	v_lshl_add_u32 v192, v192, 2, v193
	v_add_u32_e32 v193, 0x400, v192
	v_lshlrev_b32_e32 v196, 4, v196
	v_lshl_add_u32 v196, v198, 12, v196
	v_readfirstlane_b32 s8, v159
	s_lshl_b32 s9, s33, 3
	s_add_i32 s8, s8, s9
	s_waitcnt lgkmcnt(0)
	s_lshr_b32 s9, s8, 7
	s_and_b32 s10, s8, 0x7f
	s_lshl_b32 s11, s9, 21
	s_lshl_b32 s12, s10, 8
	s_add_u32 s11, s11, s12
	s_add_u32 s16, s6, s11
	s_addc_u32 s17, s7, 0
	s_lshl_b32 s11, s9, 8
	s_add_u32 s18, s4, s11
	s_addc_u32 s19, s5, 0
	s_lshl_b32 s11, s10, 18
	s_lshl_b32 s12, s9, 7
	s_add_u32 s11, s11, s12
	s_add_u32 s11, s11, 0x1000000
	s_add_u32 s20, s84, s11
	s_addc_u32 s21, s85, 0
	s_addk_i32 s8, 0x800
	s_lshr_b32 s9, s8, 7
	s_and_b32 s10, s8, 0x7f
	s_lshl_b32 s11, s9, 21
	s_lshl_b32 s12, s10, 8
	s_add_u32 s11, s11, s12
	s_add_u32 s22, s6, s11
	s_addc_u32 s23, s7, 0
	s_lshl_b32 s11, s9, 8
	s_add_u32 s24, s4, s11
	s_addc_u32 s25, s5, 0
	s_lshl_b32 s11, s10, 18
	s_lshl_b32 s12, s9, 7
	s_add_u32 s11, s11, s12
	s_add_u32 s11, s11, 0x1000000
	s_add_u32 s26, s84, s11
	s_addc_u32 s27, s85, 0
	global_load_dword v128, v195, s[18:19]
	global_load_dword v129, v195, s[18:19] offset:16
	global_load_dword v130, v195, s[18:19] offset:32
	global_load_dword v131, v195, s[18:19] offset:48
	global_load_dword v132, v195, s[18:19] offset:64
	global_load_dword v133, v195, s[18:19] offset:80
	global_load_dword v134, v195, s[18:19] offset:96
	global_load_dword v135, v195, s[18:19] offset:112
	global_load_dword v136, v195, s[18:19] offset:128
	global_load_dword v137, v195, s[18:19] offset:144
	global_load_dword v138, v195, s[18:19] offset:160
	global_load_dword v139, v195, s[18:19] offset:176
	global_load_dword v140, v195, s[18:19] offset:192
	global_load_dword v141, v195, s[18:19] offset:208
	global_load_dword v142, v195, s[18:19] offset:224
	global_load_dword v143, v195, s[18:19] offset:240
	v_mov_b32_e32 v197, v194
	global_load_dwordx4 v[0:3], v197, s[16:17] nt
	v_add_u32_e32 v197, 0x20000, v197
	global_load_dwordx4 v[4:7], v197, s[16:17] nt
	v_add_u32_e32 v197, 0x20000, v197
	global_load_dwordx4 v[8:11], v197, s[16:17] nt
	v_add_u32_e32 v197, 0x20000, v197
	global_load_dwordx4 v[12:15], v197, s[16:17] nt
	v_add_u32_e32 v197, 0x20000, v197
	global_load_dwordx4 v[16:19], v197, s[16:17] nt
	v_add_u32_e32 v197, 0x20000, v197
	global_load_dwordx4 v[20:23], v197, s[16:17] nt
	v_add_u32_e32 v197, 0x20000, v197
	global_load_dwordx4 v[24:27], v197, s[16:17] nt
	v_add_u32_e32 v197, 0x20000, v197
	global_load_dwordx4 v[28:31], v197, s[16:17] nt
	v_add_u32_e32 v197, 0x20000, v197
	global_load_dwordx4 v[32:35], v197, s[16:17] nt
	v_add_u32_e32 v197, 0x20000, v197
	global_load_dwordx4 v[36:39], v197, s[16:17] nt
	v_add_u32_e32 v197, 0x20000, v197
	global_load_dwordx4 v[40:43], v197, s[16:17] nt
	v_add_u32_e32 v197, 0x20000, v197
	global_load_dwordx4 v[44:47], v197, s[16:17] nt
	v_add_u32_e32 v197, 0x20000, v197
	global_load_dwordx4 v[48:51], v197, s[16:17] nt
	v_add_u32_e32 v197, 0x20000, v197
	global_load_dwordx4 v[52:55], v197, s[16:17] nt
	v_add_u32_e32 v197, 0x20000, v197
	global_load_dwordx4 v[56:59], v197, s[16:17] nt
	v_add_u32_e32 v197, 0x20000, v197
	global_load_dwordx4 v[60:63], v197, s[16:17] nt
	global_load_dword v160, v195, s[24:25]
	global_load_dword v161, v195, s[24:25] offset:16
	global_load_dword v162, v195, s[24:25] offset:32
	global_load_dword v163, v195, s[24:25] offset:48
	global_load_dword v164, v195, s[24:25] offset:64
	global_load_dword v165, v195, s[24:25] offset:80
	global_load_dword v166, v195, s[24:25] offset:96
	global_load_dword v167, v195, s[24:25] offset:112
	global_load_dword v168, v195, s[24:25] offset:128
	global_load_dword v169, v195, s[24:25] offset:144
	global_load_dword v170, v195, s[24:25] offset:160
	global_load_dword v171, v195, s[24:25] offset:176
	global_load_dword v172, v195, s[24:25] offset:192
	global_load_dword v173, v195, s[24:25] offset:208
	global_load_dword v174, v195, s[24:25] offset:224
	global_load_dword v175, v195, s[24:25] offset:240
	v_mov_b32_e32 v197, v194
	global_load_dwordx4 v[64:67], v197, s[22:23] nt
	v_add_u32_e32 v197, 0x20000, v197
	global_load_dwordx4 v[68:71], v197, s[22:23] nt
	v_add_u32_e32 v197, 0x20000, v197
	global_load_dwordx4 v[72:75], v197, s[22:23] nt
	v_add_u32_e32 v197, 0x20000, v197
	global_load_dwordx4 v[76:79], v197, s[22:23] nt
	v_add_u32_e32 v197, 0x20000, v197
	global_load_dwordx4 v[80:83], v197, s[22:23] nt
	v_add_u32_e32 v197, 0x20000, v197
	global_load_dwordx4 v[84:87], v197, s[22:23] nt
	v_add_u32_e32 v197, 0x20000, v197
	global_load_dwordx4 v[88:91], v197, s[22:23] nt
	v_add_u32_e32 v197, 0x20000, v197
	global_load_dwordx4 v[92:95], v197, s[22:23] nt
	v_add_u32_e32 v197, 0x20000, v197
	global_load_dwordx4 v[96:99], v197, s[22:23] nt
	v_add_u32_e32 v197, 0x20000, v197
	global_load_dwordx4 v[100:103], v197, s[22:23] nt
	v_add_u32_e32 v197, 0x20000, v197
	global_load_dwordx4 v[104:107], v197, s[22:23] nt
	v_add_u32_e32 v197, 0x20000, v197
	global_load_dwordx4 v[108:111], v197, s[22:23] nt
	v_add_u32_e32 v197, 0x20000, v197
	global_load_dwordx4 v[112:115], v197, s[22:23] nt
	v_add_u32_e32 v197, 0x20000, v197
	global_load_dwordx4 v[116:119], v197, s[22:23] nt
	v_add_u32_e32 v197, 0x20000, v197
	global_load_dwordx4 v[120:123], v197, s[22:23] nt
	v_add_u32_e32 v197, 0x20000, v197
	global_load_dwordx4 v[124:127], v197, s[22:23] nt
	s_waitcnt vmcnt(47)
	v_mul_f32_e32 v0, v0, v128
	v_mul_f32_e32 v1, v1, v128
	v_mul_f32_e32 v2, v2, v128
	v_mul_f32_e32 v3, v3, v128
	ds_write2_b32 v176, v0, v1 offset1:1
	ds_write2_b32 v176, v2, v3 offset0:2 offset1:3
	s_waitcnt vmcnt(46)
	v_mul_f32_e32 v4, v4, v129
	v_mul_f32_e32 v5, v5, v129
	v_mul_f32_e32 v6, v6, v129
	v_mul_f32_e32 v7, v7, v129
	ds_write2_b32 v177, v4, v5 offset1:1
	ds_write2_b32 v177, v6, v7 offset0:2 offset1:3
	s_waitcnt vmcnt(45)
	v_mul_f32_e32 v8, v8, v130
	v_mul_f32_e32 v9, v9, v130
	v_mul_f32_e32 v10, v10, v130
	v_mul_f32_e32 v11, v11, v130
	ds_write2_b32 v178, v8, v9 offset1:1
	ds_write2_b32 v178, v10, v11 offset0:2 offset1:3
	s_waitcnt vmcnt(44)
	v_mul_f32_e32 v12, v12, v131
	v_mul_f32_e32 v13, v13, v131
	v_mul_f32_e32 v14, v14, v131
	v_mul_f32_e32 v15, v15, v131
	ds_write2_b32 v179, v12, v13 offset1:1
	ds_write2_b32 v179, v14, v15 offset0:2 offset1:3
	s_waitcnt vmcnt(43)
	v_mul_f32_e32 v16, v16, v132
	v_mul_f32_e32 v17, v17, v132
	v_mul_f32_e32 v18, v18, v132
	v_mul_f32_e32 v19, v19, v132
	ds_write2_b32 v180, v16, v17 offset1:1
	ds_write2_b32 v180, v18, v19 offset0:2 offset1:3
	s_waitcnt vmcnt(42)
	v_mul_f32_e32 v20, v20, v133
	v_mul_f32_e32 v21, v21, v133
	v_mul_f32_e32 v22, v22, v133
	v_mul_f32_e32 v23, v23, v133
	ds_write2_b32 v181, v20, v21 offset1:1
	ds_write2_b32 v181, v22, v23 offset0:2 offset1:3
	s_waitcnt vmcnt(41)
	v_mul_f32_e32 v24, v24, v134
	v_mul_f32_e32 v25, v25, v134
	v_mul_f32_e32 v26, v26, v134
	v_mul_f32_e32 v27, v27, v134
	ds_write2_b32 v182, v24, v25 offset1:1
	ds_write2_b32 v182, v26, v27 offset0:2 offset1:3
	s_waitcnt vmcnt(40)
	v_mul_f32_e32 v28, v28, v135
	v_mul_f32_e32 v29, v29, v135
	v_mul_f32_e32 v30, v30, v135
	v_mul_f32_e32 v31, v31, v135
	ds_write2_b32 v183, v28, v29 offset1:1
	ds_write2_b32 v183, v30, v31 offset0:2 offset1:3
	s_waitcnt vmcnt(39)
	v_mul_f32_e32 v32, v32, v136
	v_mul_f32_e32 v33, v33, v136
	v_mul_f32_e32 v34, v34, v136
	v_mul_f32_e32 v35, v35, v136
	ds_write2_b32 v184, v32, v33 offset1:1
	ds_write2_b32 v184, v34, v35 offset0:2 offset1:3
	s_waitcnt vmcnt(38)
	v_mul_f32_e32 v36, v36, v137
	v_mul_f32_e32 v37, v37, v137
	v_mul_f32_e32 v38, v38, v137
	v_mul_f32_e32 v39, v39, v137
	ds_write2_b32 v185, v36, v37 offset1:1
	ds_write2_b32 v185, v38, v39 offset0:2 offset1:3
	s_waitcnt vmcnt(37)
	v_mul_f32_e32 v40, v40, v138
	v_mul_f32_e32 v41, v41, v138
	v_mul_f32_e32 v42, v42, v138
	v_mul_f32_e32 v43, v43, v138
	ds_write2_b32 v186, v40, v41 offset1:1
	ds_write2_b32 v186, v42, v43 offset0:2 offset1:3
	s_waitcnt vmcnt(36)
	v_mul_f32_e32 v44, v44, v139
	v_mul_f32_e32 v45, v45, v139
	v_mul_f32_e32 v46, v46, v139
	v_mul_f32_e32 v47, v47, v139
	ds_write2_b32 v187, v44, v45 offset1:1
	ds_write2_b32 v187, v46, v47 offset0:2 offset1:3
	s_waitcnt vmcnt(35)
	v_mul_f32_e32 v48, v48, v140
	v_mul_f32_e32 v49, v49, v140
	v_mul_f32_e32 v50, v50, v140
	v_mul_f32_e32 v51, v51, v140
	ds_write2_b32 v188, v48, v49 offset1:1
	ds_write2_b32 v188, v50, v51 offset0:2 offset1:3
	s_waitcnt vmcnt(34)
	v_mul_f32_e32 v52, v52, v141
	v_mul_f32_e32 v53, v53, v141
	v_mul_f32_e32 v54, v54, v141
	v_mul_f32_e32 v55, v55, v141
	ds_write2_b32 v189, v52, v53 offset1:1
	ds_write2_b32 v189, v54, v55 offset0:2 offset1:3
	s_waitcnt vmcnt(33)
	v_mul_f32_e32 v56, v56, v142
	v_mul_f32_e32 v57, v57, v142
	v_mul_f32_e32 v58, v58, v142
	v_mul_f32_e32 v59, v59, v142
	ds_write2_b32 v190, v56, v57 offset1:1
	ds_write2_b32 v190, v58, v59 offset0:2 offset1:3
	s_waitcnt vmcnt(32)
	v_mul_f32_e32 v60, v60, v143
	v_mul_f32_e32 v61, v61, v143
	v_mul_f32_e32 v62, v62, v143
	v_mul_f32_e32 v63, v63, v143
	ds_write2_b32 v191, v60, v61 offset1:1
	ds_write2_b32 v191, v62, v63 offset0:2 offset1:3
	s_waitcnt lgkmcnt(0)
	v_mov_b32_e32 v197, v196
	ds_read2_b32 v[208:209], v192 offset0:0 offset1:65
	ds_read2_b32 v[210:211], v192 offset0:130 offset1:195
	ds_read2_b32 v[212:213], v193 offset0:4 offset1:69
	ds_read2_b32 v[214:215], v193 offset0:134 offset1:199
	ds_read2_b32 v[216:217], v192 offset0:8 offset1:73
	ds_read2_b32 v[218:219], v192 offset0:138 offset1:203
	ds_read2_b32 v[220:221], v193 offset0:12 offset1:77
	ds_read2_b32 v[222:223], v193 offset0:142 offset1:207
	s_waitcnt lgkmcnt(4)
	v_cvt_pk_bf16_f32 v200, v208, v209
	v_cvt_pk_bf16_f32 v201, v210, v211
	v_cvt_pk_bf16_f32 v202, v212, v213
	v_cvt_pk_bf16_f32 v203, v214, v215
	global_store_dwordx4 v197, v[200:203], s[20:21] sc0 sc1 nt
	v_add_u32_e32 v197, 0x8000, v197
	s_waitcnt lgkmcnt(0)
	v_cvt_pk_bf16_f32 v204, v216, v217
	v_cvt_pk_bf16_f32 v205, v218, v219
	v_cvt_pk_bf16_f32 v206, v220, v221
	v_cvt_pk_bf16_f32 v207, v222, v223
	global_store_dwordx4 v197, v[204:207], s[20:21] sc0 sc1 nt
	v_add_u32_e32 v197, 0x8000, v197
	ds_read2_b32 v[208:209], v192 offset0:16 offset1:81
	ds_read2_b32 v[210:211], v192 offset0:146 offset1:211
	ds_read2_b32 v[212:213], v193 offset0:20 offset1:85
	ds_read2_b32 v[214:215], v193 offset0:150 offset1:215
	ds_read2_b32 v[216:217], v192 offset0:24 offset1:89
	ds_read2_b32 v[218:219], v192 offset0:154 offset1:219
	ds_read2_b32 v[220:221], v193 offset0:28 offset1:93
	ds_read2_b32 v[222:223], v193 offset0:158 offset1:223
	s_waitcnt lgkmcnt(4)
	v_cvt_pk_bf16_f32 v200, v208, v209
	v_cvt_pk_bf16_f32 v201, v210, v211
	v_cvt_pk_bf16_f32 v202, v212, v213
	v_cvt_pk_bf16_f32 v203, v214, v215
	global_store_dwordx4 v197, v[200:203], s[20:21] sc0 sc1 nt
	v_add_u32_e32 v197, 0x8000, v197
	s_waitcnt lgkmcnt(0)
	v_cvt_pk_bf16_f32 v204, v216, v217
	v_cvt_pk_bf16_f32 v205, v218, v219
	v_cvt_pk_bf16_f32 v206, v220, v221
	v_cvt_pk_bf16_f32 v207, v222, v223
	global_store_dwordx4 v197, v[204:207], s[20:21] sc0 sc1 nt
	v_add_u32_e32 v197, 0x8000, v197
	ds_read2_b32 v[208:209], v192 offset0:32 offset1:97
	ds_read2_b32 v[210:211], v192 offset0:162 offset1:227
	ds_read2_b32 v[212:213], v193 offset0:36 offset1:101
	ds_read2_b32 v[214:215], v193 offset0:166 offset1:231
	ds_read2_b32 v[216:217], v192 offset0:40 offset1:105
	ds_read2_b32 v[218:219], v192 offset0:170 offset1:235
	ds_read2_b32 v[220:221], v193 offset0:44 offset1:109
	ds_read2_b32 v[222:223], v193 offset0:174 offset1:239
	s_waitcnt lgkmcnt(4)
	v_cvt_pk_bf16_f32 v200, v208, v209
	v_cvt_pk_bf16_f32 v201, v210, v211
	v_cvt_pk_bf16_f32 v202, v212, v213
	v_cvt_pk_bf16_f32 v203, v214, v215
	global_store_dwordx4 v197, v[200:203], s[20:21] sc0 sc1 nt
	v_add_u32_e32 v197, 0x8000, v197
	s_waitcnt lgkmcnt(0)
	v_cvt_pk_bf16_f32 v204, v216, v217
	v_cvt_pk_bf16_f32 v205, v218, v219
	v_cvt_pk_bf16_f32 v206, v220, v221
	v_cvt_pk_bf16_f32 v207, v222, v223
	global_store_dwordx4 v197, v[204:207], s[20:21] sc0 sc1 nt
	v_add_u32_e32 v197, 0x8000, v197
	ds_read2_b32 v[208:209], v192 offset0:48 offset1:113
	ds_read2_b32 v[210:211], v192 offset0:178 offset1:243
	ds_read2_b32 v[212:213], v193 offset0:52 offset1:117
	ds_read2_b32 v[214:215], v193 offset0:182 offset1:247
	ds_read2_b32 v[216:217], v192 offset0:56 offset1:121
	ds_read2_b32 v[218:219], v192 offset0:186 offset1:251
	ds_read2_b32 v[220:221], v193 offset0:60 offset1:125
	ds_read2_b32 v[222:223], v193 offset0:190 offset1:255
	s_waitcnt lgkmcnt(4)
	v_cvt_pk_bf16_f32 v200, v208, v209
	v_cvt_pk_bf16_f32 v201, v210, v211
	v_cvt_pk_bf16_f32 v202, v212, v213
	v_cvt_pk_bf16_f32 v203, v214, v215
	global_store_dwordx4 v197, v[200:203], s[20:21] sc0 sc1 nt
	v_add_u32_e32 v197, 0x8000, v197
	s_waitcnt lgkmcnt(0)
	v_cvt_pk_bf16_f32 v204, v216, v217
	v_cvt_pk_bf16_f32 v205, v218, v219
	v_cvt_pk_bf16_f32 v206, v220, v221
	v_cvt_pk_bf16_f32 v207, v222, v223
	global_store_dwordx4 v197, v[204:207], s[20:21] sc0 sc1 nt
	v_add_u32_e32 v197, 0x8000, v197
	s_waitcnt lgkmcnt(0)
	s_waitcnt vmcnt(23)
	v_mul_f32_e32 v64, v64, v160
	v_mul_f32_e32 v65, v65, v160
	v_mul_f32_e32 v66, v66, v160
	v_mul_f32_e32 v67, v67, v160
	ds_write2_b32 v176, v64, v65 offset1:1
	ds_write2_b32 v176, v66, v67 offset0:2 offset1:3
	s_waitcnt vmcnt(22)
	v_mul_f32_e32 v68, v68, v161
	v_mul_f32_e32 v69, v69, v161
	v_mul_f32_e32 v70, v70, v161
	v_mul_f32_e32 v71, v71, v161
	ds_write2_b32 v177, v68, v69 offset1:1
	ds_write2_b32 v177, v70, v71 offset0:2 offset1:3
	s_waitcnt vmcnt(21)
	v_mul_f32_e32 v72, v72, v162
	v_mul_f32_e32 v73, v73, v162
	v_mul_f32_e32 v74, v74, v162
	v_mul_f32_e32 v75, v75, v162
	ds_write2_b32 v178, v72, v73 offset1:1
	ds_write2_b32 v178, v74, v75 offset0:2 offset1:3
	s_waitcnt vmcnt(20)
	v_mul_f32_e32 v76, v76, v163
	v_mul_f32_e32 v77, v77, v163
	v_mul_f32_e32 v78, v78, v163
	v_mul_f32_e32 v79, v79, v163
	ds_write2_b32 v179, v76, v77 offset1:1
	ds_write2_b32 v179, v78, v79 offset0:2 offset1:3
	s_waitcnt vmcnt(19)
	v_mul_f32_e32 v80, v80, v164
	v_mul_f32_e32 v81, v81, v164
	v_mul_f32_e32 v82, v82, v164
	v_mul_f32_e32 v83, v83, v164
	ds_write2_b32 v180, v80, v81 offset1:1
	ds_write2_b32 v180, v82, v83 offset0:2 offset1:3
	s_waitcnt vmcnt(18)
	v_mul_f32_e32 v84, v84, v165
	v_mul_f32_e32 v85, v85, v165
	v_mul_f32_e32 v86, v86, v165
	v_mul_f32_e32 v87, v87, v165
	ds_write2_b32 v181, v84, v85 offset1:1
	ds_write2_b32 v181, v86, v87 offset0:2 offset1:3
	s_waitcnt vmcnt(17)
	v_mul_f32_e32 v88, v88, v166
	v_mul_f32_e32 v89, v89, v166
	v_mul_f32_e32 v90, v90, v166
	v_mul_f32_e32 v91, v91, v166
	ds_write2_b32 v182, v88, v89 offset1:1
	ds_write2_b32 v182, v90, v91 offset0:2 offset1:3
	s_waitcnt vmcnt(16)
	v_mul_f32_e32 v92, v92, v167
	v_mul_f32_e32 v93, v93, v167
	v_mul_f32_e32 v94, v94, v167
	v_mul_f32_e32 v95, v95, v167
	ds_write2_b32 v183, v92, v93 offset1:1
	ds_write2_b32 v183, v94, v95 offset0:2 offset1:3
	s_waitcnt vmcnt(15)
	v_mul_f32_e32 v96, v96, v168
	v_mul_f32_e32 v97, v97, v168
	v_mul_f32_e32 v98, v98, v168
	v_mul_f32_e32 v99, v99, v168
	ds_write2_b32 v184, v96, v97 offset1:1
	ds_write2_b32 v184, v98, v99 offset0:2 offset1:3
	s_waitcnt vmcnt(14)
	v_mul_f32_e32 v100, v100, v169
	v_mul_f32_e32 v101, v101, v169
	v_mul_f32_e32 v102, v102, v169
	v_mul_f32_e32 v103, v103, v169
	ds_write2_b32 v185, v100, v101 offset1:1
	ds_write2_b32 v185, v102, v103 offset0:2 offset1:3
	s_waitcnt vmcnt(13)
	v_mul_f32_e32 v104, v104, v170
	v_mul_f32_e32 v105, v105, v170
	v_mul_f32_e32 v106, v106, v170
	v_mul_f32_e32 v107, v107, v170
	ds_write2_b32 v186, v104, v105 offset1:1
	ds_write2_b32 v186, v106, v107 offset0:2 offset1:3
	s_waitcnt vmcnt(12)
	v_mul_f32_e32 v108, v108, v171
	v_mul_f32_e32 v109, v109, v171
	v_mul_f32_e32 v110, v110, v171
	v_mul_f32_e32 v111, v111, v171
	ds_write2_b32 v187, v108, v109 offset1:1
	ds_write2_b32 v187, v110, v111 offset0:2 offset1:3
	s_waitcnt vmcnt(11)
	v_mul_f32_e32 v112, v112, v172
	v_mul_f32_e32 v113, v113, v172
	v_mul_f32_e32 v114, v114, v172
	v_mul_f32_e32 v115, v115, v172
	ds_write2_b32 v188, v112, v113 offset1:1
	ds_write2_b32 v188, v114, v115 offset0:2 offset1:3
	s_waitcnt vmcnt(10)
	v_mul_f32_e32 v116, v116, v173
	v_mul_f32_e32 v117, v117, v173
	v_mul_f32_e32 v118, v118, v173
	v_mul_f32_e32 v119, v119, v173
	ds_write2_b32 v189, v116, v117 offset1:1
	ds_write2_b32 v189, v118, v119 offset0:2 offset1:3
	s_waitcnt vmcnt(9)
	v_mul_f32_e32 v120, v120, v174
	v_mul_f32_e32 v121, v121, v174
	v_mul_f32_e32 v122, v122, v174
	v_mul_f32_e32 v123, v123, v174
	ds_write2_b32 v190, v120, v121 offset1:1
	ds_write2_b32 v190, v122, v123 offset0:2 offset1:3
	s_waitcnt vmcnt(8)
	v_mul_f32_e32 v124, v124, v175
	v_mul_f32_e32 v125, v125, v175
	v_mul_f32_e32 v126, v126, v175
	v_mul_f32_e32 v127, v127, v175
	ds_write2_b32 v191, v124, v125 offset1:1
	ds_write2_b32 v191, v126, v127 offset0:2 offset1:3
	s_waitcnt lgkmcnt(0)
	v_mov_b32_e32 v197, v196
	ds_read2_b32 v[208:209], v192 offset0:0 offset1:65
	ds_read2_b32 v[210:211], v192 offset0:130 offset1:195
	ds_read2_b32 v[212:213], v193 offset0:4 offset1:69
	ds_read2_b32 v[214:215], v193 offset0:134 offset1:199
	ds_read2_b32 v[216:217], v192 offset0:8 offset1:73
	ds_read2_b32 v[218:219], v192 offset0:138 offset1:203
	ds_read2_b32 v[220:221], v193 offset0:12 offset1:77
	ds_read2_b32 v[222:223], v193 offset0:142 offset1:207
	s_waitcnt lgkmcnt(4)
	v_cvt_pk_bf16_f32 v200, v208, v209
	v_cvt_pk_bf16_f32 v201, v210, v211
	v_cvt_pk_bf16_f32 v202, v212, v213
	v_cvt_pk_bf16_f32 v203, v214, v215
	global_store_dwordx4 v197, v[200:203], s[26:27] sc0 sc1 nt
	v_add_u32_e32 v197, 0x8000, v197
	s_waitcnt lgkmcnt(0)
	v_cvt_pk_bf16_f32 v204, v216, v217
	v_cvt_pk_bf16_f32 v205, v218, v219
	v_cvt_pk_bf16_f32 v206, v220, v221
	v_cvt_pk_bf16_f32 v207, v222, v223
	global_store_dwordx4 v197, v[204:207], s[26:27] sc0 sc1 nt
	v_add_u32_e32 v197, 0x8000, v197
	ds_read2_b32 v[208:209], v192 offset0:16 offset1:81
	ds_read2_b32 v[210:211], v192 offset0:146 offset1:211
	ds_read2_b32 v[212:213], v193 offset0:20 offset1:85
	ds_read2_b32 v[214:215], v193 offset0:150 offset1:215
	ds_read2_b32 v[216:217], v192 offset0:24 offset1:89
	ds_read2_b32 v[218:219], v192 offset0:154 offset1:219
	ds_read2_b32 v[220:221], v193 offset0:28 offset1:93
	ds_read2_b32 v[222:223], v193 offset0:158 offset1:223
	s_waitcnt lgkmcnt(4)
	v_cvt_pk_bf16_f32 v200, v208, v209
	v_cvt_pk_bf16_f32 v201, v210, v211
	v_cvt_pk_bf16_f32 v202, v212, v213
	v_cvt_pk_bf16_f32 v203, v214, v215
	global_store_dwordx4 v197, v[200:203], s[26:27] sc0 sc1 nt
	v_add_u32_e32 v197, 0x8000, v197
	s_waitcnt lgkmcnt(0)
	v_cvt_pk_bf16_f32 v204, v216, v217
	v_cvt_pk_bf16_f32 v205, v218, v219
	v_cvt_pk_bf16_f32 v206, v220, v221
	v_cvt_pk_bf16_f32 v207, v222, v223
	global_store_dwordx4 v197, v[204:207], s[26:27] sc0 sc1 nt
	v_add_u32_e32 v197, 0x8000, v197
	ds_read2_b32 v[208:209], v192 offset0:32 offset1:97
	ds_read2_b32 v[210:211], v192 offset0:162 offset1:227
	ds_read2_b32 v[212:213], v193 offset0:36 offset1:101
	ds_read2_b32 v[214:215], v193 offset0:166 offset1:231
	ds_read2_b32 v[216:217], v192 offset0:40 offset1:105
	ds_read2_b32 v[218:219], v192 offset0:170 offset1:235
	ds_read2_b32 v[220:221], v193 offset0:44 offset1:109
	ds_read2_b32 v[222:223], v193 offset0:174 offset1:239
	s_waitcnt lgkmcnt(4)
	v_cvt_pk_bf16_f32 v200, v208, v209
	v_cvt_pk_bf16_f32 v201, v210, v211
	v_cvt_pk_bf16_f32 v202, v212, v213
	v_cvt_pk_bf16_f32 v203, v214, v215
	global_store_dwordx4 v197, v[200:203], s[26:27] sc0 sc1 nt
	v_add_u32_e32 v197, 0x8000, v197
	s_waitcnt lgkmcnt(0)
	v_cvt_pk_bf16_f32 v204, v216, v217
	v_cvt_pk_bf16_f32 v205, v218, v219
	v_cvt_pk_bf16_f32 v206, v220, v221
	v_cvt_pk_bf16_f32 v207, v222, v223
	global_store_dwordx4 v197, v[204:207], s[26:27] sc0 sc1 nt
	v_add_u32_e32 v197, 0x8000, v197
	ds_read2_b32 v[208:209], v192 offset0:48 offset1:113
	ds_read2_b32 v[210:211], v192 offset0:178 offset1:243
	ds_read2_b32 v[212:213], v193 offset0:52 offset1:117
	ds_read2_b32 v[214:215], v193 offset0:182 offset1:247
	ds_read2_b32 v[216:217], v192 offset0:56 offset1:121
	ds_read2_b32 v[218:219], v192 offset0:186 offset1:251
	ds_read2_b32 v[220:221], v193 offset0:60 offset1:125
	ds_read2_b32 v[222:223], v193 offset0:190 offset1:255
	s_waitcnt lgkmcnt(4)
	v_cvt_pk_bf16_f32 v200, v208, v209
	v_cvt_pk_bf16_f32 v201, v210, v211
	v_cvt_pk_bf16_f32 v202, v212, v213
	v_cvt_pk_bf16_f32 v203, v214, v215
	global_store_dwordx4 v197, v[200:203], s[26:27] sc0 sc1 nt
	v_add_u32_e32 v197, 0x8000, v197
	s_waitcnt lgkmcnt(0)
	v_cvt_pk_bf16_f32 v204, v216, v217
	v_cvt_pk_bf16_f32 v205, v218, v219
	v_cvt_pk_bf16_f32 v206, v220, v221
	v_cvt_pk_bf16_f32 v207, v222, v223
	global_store_dwordx4 v197, v[204:207], s[26:27] sc0 sc1 nt
	v_add_u32_e32 v197, 0x8000, v197

.Lmy_cv_wr:
	v_ashrrev_i32_e32 v5, 31, v4
	v_ashrrev_i32_e32 v7, 31, v6
	v_lshl_add_u64 v[4:5], v[4:5], 1, v[2:3]
	v_lshlrev_b64 v[122:123], 14, v[6:7]
	v_add_u32_e32 v110, 8, v6
	v_lshl_add_u64 v[122:123], v[4:5], 0, v[122:123]
	v_ashrrev_i32_e32 v111, 31, v110
	v_lshlrev_b64 v[110:111], 14, v[110:111]
	v_add_u32_e32 v112, 16, v6
	v_lshl_add_u64 v[110:111], v[4:5], 0, v[110:111]
	v_ashrrev_i32_e32 v113, 31, v112
	v_lshlrev_b64 v[112:113], 14, v[112:113]
	v_add_u32_e32 v114, 24, v6
	v_lshl_add_u64 v[112:113], v[4:5], 0, v[112:113]
	ds_write2_b32 v13, v46, v47 offset1:1
	ds_write2_b32 v13, v48, v49 offset0:2 offset1:3
	ds_write2_b32 v14, v50, v51 offset1:1
	ds_write2_b32 v15, v52, v53 offset1:1
	ds_write2_b32 v16, v54, v55 offset1:1
	ds_write2_b32 v17, v56, v57 offset1:1
	ds_write2_b32 v18, v58, v59 offset1:1
	ds_write2_b32 v19, v60, v61 offset1:1
	ds_write2_b32 v20, v62, v63 offset1:1
	ds_write2_b32 v21, v64, v65 offset1:1
	ds_write2_b32 v22, v66, v67 offset1:1
	ds_write2_b32 v23, v68, v69 offset1:1
	ds_write2_b32 v24, v70, v71 offset1:1
	ds_write2_b32 v25, v72, v73 offset1:1
	ds_write2_b32 v26, v74, v75 offset1:1
	ds_write2_b32 v27, v76, v77 offset1:1
	ds_write2_b32 v28, v78, v79 offset1:1
	ds_write2_b32 v29, v80, v81 offset1:1
	ds_write2_b32 v30, v82, v83 offset1:1
	ds_write2_b32 v31, v84, v85 offset1:1
	ds_write2_b32 v32, v86, v87 offset1:1
	ds_write2_b32 v33, v88, v89 offset1:1
	ds_write2_b32 v34, v90, v91 offset1:1
	ds_write2_b32 v35, v92, v93 offset1:1
	ds_write2_b32 v36, v94, v95 offset1:1
	ds_write2_b32 v37, v96, v97 offset1:1
	ds_write2_b32 v38, v98, v99 offset1:1
	ds_write2_b32 v39, v100, v101 offset1:1
	ds_write2_b32 v40, v102, v103 offset1:1
	ds_write2_b32 v41, v104, v105 offset1:1
	ds_write2_b32 v42, v106, v107 offset1:1
	ds_write2_b32 v43, v108, v109 offset1:1
	s_waitcnt lgkmcnt(0)
	ds_read2_b32 v[46:47], v11 offset1:65
	s_waitcnt lgkmcnt(0)
	v_cvt_pk_bf16_f32 v46, v46, v47
	ds_read2_b32 v[48:49], v11 offset0:130 offset1:195
	s_waitcnt lgkmcnt(0)
	v_cvt_pk_bf16_f32 v47, v48, v49
	ds_read2_b32 v[48:49], v44 offset0:4 offset1:69
	s_waitcnt lgkmcnt(0)
	v_cvt_pk_bf16_f32 v48, v48, v49
	ds_read2_b32 v[50:51], v44 offset0:134 offset1:199
	s_waitcnt lgkmcnt(0)
	v_cvt_pk_bf16_f32 v49, v50, v51
	ds_read2_b32 v[50:51], v11 offset0:8 offset1:73
	global_store_dwordx4 v[122:123], v[46:49], off sc0 sc1 nt
	v_ashrrev_i32_e32 v115, 31, v114
	v_lshlrev_b64 v[114:115], 14, v[114:115]
	s_waitcnt lgkmcnt(0)
	v_cvt_pk_bf16_f32 v46, v50, v51
	ds_read2_b32 v[48:49], v11 offset0:138 offset1:203
	s_waitcnt lgkmcnt(0)
	v_cvt_pk_bf16_f32 v47, v48, v49
	ds_read2_b32 v[48:49], v44 offset0:12 offset1:77
	s_waitcnt lgkmcnt(0)
	v_cvt_pk_bf16_f32 v48, v48, v49
	ds_read2_b32 v[50:51], v44 offset0:142 offset1:207
	s_waitcnt lgkmcnt(0)
	v_cvt_pk_bf16_f32 v49, v50, v51
	ds_read2_b32 v[50:51], v11 offset0:16 offset1:81
	global_store_dwordx4 v[110:111], v[46:49], off sc0 sc1 nt
	v_add_u32_e32 v116, 32, v6
	v_lshl_add_u64 v[114:115], v[4:5], 0, v[114:115]
	s_waitcnt lgkmcnt(0)
	v_cvt_pk_bf16_f32 v46, v50, v51
	ds_read2_b32 v[48:49], v11 offset0:146 offset1:211
	s_waitcnt lgkmcnt(0)
	v_cvt_pk_bf16_f32 v47, v48, v49
	ds_read2_b32 v[48:49], v44 offset0:20 offset1:85
	s_waitcnt lgkmcnt(0)
	v_cvt_pk_bf16_f32 v48, v48, v49
	ds_read2_b32 v[50:51], v44 offset0:150 offset1:215
	s_waitcnt lgkmcnt(0)
	v_cvt_pk_bf16_f32 v49, v50, v51
	ds_read2_b32 v[50:51], v11 offset0:24 offset1:89
	global_store_dwordx4 v[112:113], v[46:49], off sc0 sc1 nt
	v_ashrrev_i32_e32 v117, 31, v116
	v_lshlrev_b64 v[116:117], 14, v[116:117]
	s_waitcnt lgkmcnt(0)
	v_cvt_pk_bf16_f32 v46, v50, v51
	ds_read2_b32 v[48:49], v11 offset0:154 offset1:219
	s_waitcnt lgkmcnt(0)
	v_cvt_pk_bf16_f32 v47, v48, v49
	ds_read2_b32 v[48:49], v44 offset0:28 offset1:93
	s_waitcnt lgkmcnt(0)
	v_cvt_pk_bf16_f32 v48, v48, v49
	ds_read2_b32 v[50:51], v44 offset0:158 offset1:223
	s_waitcnt lgkmcnt(0)
	v_cvt_pk_bf16_f32 v49, v50, v51
	ds_read2_b32 v[50:51], v11 offset0:32 offset1:97
	global_store_dwordx4 v[114:115], v[46:49], off sc0 sc1 nt
	v_add_u32_e32 v118, 40, v6
	v_lshl_add_u64 v[116:117], v[4:5], 0, v[116:117]
	s_waitcnt lgkmcnt(0)
	v_cvt_pk_bf16_f32 v46, v50, v51
	ds_read2_b32 v[48:49], v11 offset0:162 offset1:227
	s_waitcnt lgkmcnt(0)
	v_cvt_pk_bf16_f32 v47, v48, v49
	ds_read2_b32 v[48:49], v44 offset0:36 offset1:101
	s_waitcnt lgkmcnt(0)
	v_cvt_pk_bf16_f32 v48, v48, v49
	ds_read2_b32 v[50:51], v44 offset0:166 offset1:231
	s_waitcnt lgkmcnt(0)
	v_cvt_pk_bf16_f32 v49, v50, v51
	v_ashrrev_i32_e32 v119, 31, v118
	ds_read2_b32 v[50:51], v11 offset0:40 offset1:105
	global_store_dwordx4 v[116:117], v[46:49], off sc0 sc1 nt
	v_lshlrev_b64 v[118:119], 14, v[118:119]
	v_add_u32_e32 v120, 48, v6
	s_waitcnt lgkmcnt(0)
	v_cvt_pk_bf16_f32 v46, v50, v51
	ds_read2_b32 v[48:49], v11 offset0:170 offset1:235
	s_waitcnt lgkmcnt(0)
	v_cvt_pk_bf16_f32 v47, v48, v49
	ds_read2_b32 v[48:49], v44 offset0:44 offset1:109
	v_lshl_add_u64 v[118:119], v[4:5], 0, v[118:119]
	s_waitcnt lgkmcnt(0)
	v_cvt_pk_bf16_f32 v48, v48, v49
	ds_read2_b32 v[50:51], v44 offset0:174 offset1:239
	s_waitcnt lgkmcnt(0)
	v_cvt_pk_bf16_f32 v49, v50, v51
	v_ashrrev_i32_e32 v121, 31, v120
	ds_read2_b32 v[50:51], v11 offset0:48 offset1:113
	global_store_dwordx4 v[118:119], v[46:49], off sc0 sc1 nt
	v_lshlrev_b64 v[120:121], 14, v[120:121]
	v_add_u32_e32 v6, 56, v6
	s_waitcnt lgkmcnt(0)
	v_cvt_pk_bf16_f32 v46, v50, v51
	ds_read2_b32 v[48:49], v11 offset0:178 offset1:243
	s_waitcnt lgkmcnt(0)
	v_cvt_pk_bf16_f32 v47, v48, v49
	ds_read2_b32 v[48:49], v44 offset0:52 offset1:117
	v_lshl_add_u64 v[120:121], v[4:5], 0, v[120:121]
	s_waitcnt lgkmcnt(0)
	v_cvt_pk_bf16_f32 v48, v48, v49
	ds_read2_b32 v[50:51], v44 offset0:182 offset1:247
	s_waitcnt lgkmcnt(0)
	v_cvt_pk_bf16_f32 v49, v50, v51
	v_ashrrev_i32_e32 v7, 31, v6
	ds_read2_b32 v[50:51], v11 offset0:56 offset1:121
	global_store_dwordx4 v[120:121], v[46:49], off sc0 sc1 nt
	v_lshlrev_b64 v[6:7], 14, v[6:7]
	v_lshl_add_u64 v[4:5], v[4:5], 0, v[6:7]
	s_waitcnt lgkmcnt(0)
	v_cvt_pk_bf16_f32 v46, v50, v51
	ds_read2_b32 v[48:49], v11 offset0:186 offset1:251
	s_waitcnt lgkmcnt(0)
	v_cvt_pk_bf16_f32 v47, v48, v49
	ds_read2_b32 v[48:49], v44 offset0:60 offset1:125
	s_waitcnt lgkmcnt(0)
	v_cvt_pk_bf16_f32 v48, v48, v49
	ds_read2_b32 v[50:51], v44 offset0:190 offset1:255
	s_waitcnt lgkmcnt(0)
	v_cvt_pk_bf16_f32 v49, v50, v51
	global_store_dwordx4 v[4:5], v[46:49], off sc0 sc1 nt
	s_waitcnt lgkmcnt(0)
	v_cmp_gt_i32_e32 vcc, s5, v132
	s_cbranch_vccz .LBB0_1257
	s_waitcnt vmcnt(8)
	v_mov_b32_e32 v46, v160
	v_mov_b32_e32 v47, v161
	v_mov_b32_e32 v48, v162
	v_mov_b32_e32 v49, v163
	v_mov_b32_e32 v50, v164
	v_mov_b32_e32 v51, v165
	v_mov_b32_e32 v52, v166
	v_mov_b32_e32 v53, v167
	v_mov_b32_e32 v54, v168
	v_mov_b32_e32 v55, v169
	v_mov_b32_e32 v56, v170
	v_mov_b32_e32 v57, v171
	v_mov_b32_e32 v58, v172
	v_mov_b32_e32 v59, v173
	v_mov_b32_e32 v60, v174
	v_mov_b32_e32 v61, v175
	v_mov_b32_e32 v62, v176
	v_mov_b32_e32 v63, v177
	v_mov_b32_e32 v64, v178
	v_mov_b32_e32 v65, v179
	v_mov_b32_e32 v66, v180
	v_mov_b32_e32 v67, v181
	v_mov_b32_e32 v68, v182
	v_mov_b32_e32 v69, v183
	v_mov_b32_e32 v70, v184
	v_mov_b32_e32 v71, v185
	v_mov_b32_e32 v72, v186
	v_mov_b32_e32 v73, v187
	v_mov_b32_e32 v74, v188
	v_mov_b32_e32 v75, v189
	v_mov_b32_e32 v76, v190
	v_mov_b32_e32 v77, v191
	v_mov_b32_e32 v78, v192
	v_mov_b32_e32 v79, v193
	v_mov_b32_e32 v80, v194
	v_mov_b32_e32 v81, v195
	v_mov_b32_e32 v82, v196
	v_mov_b32_e32 v83, v197
	v_mov_b32_e32 v84, v198
	v_mov_b32_e32 v85, v199
	v_mov_b32_e32 v86, v200
	v_mov_b32_e32 v87, v201
	v_mov_b32_e32 v88, v202
	v_mov_b32_e32 v89, v203
	v_mov_b32_e32 v90, v204
	v_mov_b32_e32 v91, v205
	v_mov_b32_e32 v92, v206
	v_mov_b32_e32 v93, v207
	v_mov_b32_e32 v94, v208
	v_mov_b32_e32 v95, v209
	v_mov_b32_e32 v96, v210
	v_mov_b32_e32 v97, v211
	v_mov_b32_e32 v98, v212
	v_mov_b32_e32 v99, v213
	v_mov_b32_e32 v100, v214
	v_mov_b32_e32 v101, v215
	v_mov_b32_e32 v102, v216
	v_mov_b32_e32 v103, v217
	v_mov_b32_e32 v104, v218
	v_mov_b32_e32 v105, v219
	v_mov_b32_e32 v106, v220
	v_mov_b32_e32 v107, v221
	v_mov_b32_e32 v108, v222
	v_mov_b32_e32 v109, v223
	v_mov_b32_e32 v4, v246
	v_mov_b32_e32 v6, v248
	v_mov_b32_e32 v8, v132
	v_mov_b32_e32 v12, v133
	s_branch .Lmy_cv_loop
